# v63 + three 4-byte pads so every hot loop head keeps the baseline's byte phase (offset mod 8 = 4)
# baseline (speedup 1.0000x reference)
.LBB0_250:
	s_nop 0
	s_or_b64 exec, exec, s[50:51]
	s_andn2_b64 vcc, exec, s[46:47]
	s_mov_b64 s[28:29], -1
	s_cbranch_vccnz .LBB0_225
	s_andn2_b64 vcc, exec, s[38:39]
	s_cbranch_vccnz .LBB0_224
	s_barrier
	s_branch .LBB0_224

.LBB0_355:
	s_nop 0
	s_lshl_b32 s2, s97, 6
	v_readlane_b32 s3, v235, 25
	s_add_i32 s2, s2, s3
	s_ashr_i32 s3, s2, 31
	s_lshl_b64 s[2:3], s[2:3], 2
	v_readlane_b32 s4, v236, 36
	v_readlane_b32 s5, v236, 37
	s_add_u32 s42, s4, s2
	s_addc_u32 s43, s5, s3
	s_lshl_b32 s44, s97, 3
	s_ashr_i32 s45, s44, 31
	s_lshl_b64 s[2:3], s[44:45], 21
	v_readlane_b32 s4, v235, 26
	s_add_u32 s31, s4, s2
	v_readlane_b32 s4, v235, 27
	s_addc_u32 s45, s4, s3
	v_readlane_b32 s4, v235, 28
	s_add_u32 s50, s4, s2
	v_readlane_b32 s4, v235, 29
	s_addc_u32 s51, s4, s3
	v_readlane_b32 s4, v235, 32
	s_add_u32 s84, s4, s2
	v_readlane_b32 s4, v235, 33
	s_addc_u32 s85, s4, s3
	v_readlane_b32 s4, v235, 34
	s_add_u32 s86, s4, s2
	v_readlane_b32 s4, v235, 35
	s_addc_u32 s87, s4, s3
	v_readlane_b32 s4, v235, 38
	s_add_u32 s46, s4, s2
	v_readlane_b32 s4, v235, 39
	s_addc_u32 s47, s4, s3
	v_readlane_b32 s4, v236, 48
	s_add_u32 s88, s4, s2
	v_readlane_b32 s2, v236, 49
	s_addc_u32 s89, s2, s3
	s_mov_b64 s[40:41], 0
	s_mov_b32 s95, 0
	s_mov_b32 s94, 0
	s_mov_b32 s93, 0
	s_mov_b32 s92, 0
	s_branch .LBB0_357

.LBB0_434:
	s_nop 0
	v_mov_b64_e32 v[34:35], v[50:51]
	v_mov_b64_e32 v[36:37], v[52:53]
	v_mov_b64_e32 v[38:39], v[54:55]
	v_mov_b64_e32 v[40:41], v[56:57]
	v_mov_b64_e32 v[42:43], v[58:59]
	v_mov_b64_e32 v[44:45], v[60:61]
	v_mov_b64_e32 v[46:47], v[62:63]
	v_mov_b64_e32 v[48:49], v[64:65]
	v_add_u32_e32 v90, s59, v134
	ds_read_b128 v[82:85], v90
	v_exp_f32_e32 v94, v66
	v_exp_f32_e32 v95, v67
	v_exp_f32_e32 v96, v68
	v_exp_f32_e32 v97, v69
	v_exp_f32_e32 v130, v70
	v_exp_f32_e32 v131, v71
	v_exp_f32_e32 v134, v72
	v_exp_f32_e32 v135, v73
	s_waitcnt lgkmcnt(0)
	v_mfma_f32_32x32x16_bf16 v[50:65], v[82:85], v[118:121], v[34:49]
	ds_read_b128 v[82:85], v90 offset:2048
	ds_read_b128 v[86:89], v90 offset:4096
	ds_read_b128 v[66:69], v90 offset:6144
	ds_read_b128 v[70:73], v90 offset:8192
	v_exp_f32_e32 v153, v74
	v_exp_f32_e32 v154, v75
	v_exp_f32_e32 v155, v76
	v_exp_f32_e32 v156, v77
	s_waitcnt lgkmcnt(3)
	v_mfma_f32_32x32x16_bf16 v[50:65], v[82:85], v[114:117], v[50:65]
	v_exp_f32_e32 v157, v78
	v_exp_f32_e32 v158, v79
	v_exp_f32_e32 v159, v80
	v_exp_f32_e32 v160, v81
	v_add_f32_e32 v161, v141, v146
	v_add_f32_e32 v161, v138, v161
	v_add_f32_e32 v161, v142, v161
	s_waitcnt lgkmcnt(2)
	v_mfma_f32_32x32x16_bf16 v[50:65], v[86:89], v[110:113], v[50:65]
	s_waitcnt lgkmcnt(1)
	v_mfma_f32_32x32x16_bf16 v[50:65], v[66:69], v[106:109], v[50:65]
	ds_read_b128 v[66:69], v90 offset:512
	ds_read_b128 v[74:77], v90 offset:10240
	s_waitcnt lgkmcnt(1)
	v_mfma_f32_32x32x16_bf16 v[34:49], v[66:69], v[118:121], v[34:49]
	v_cvt_pk_bf16_f32 v68, v143, v147
	v_cvt_pk_bf16_f32 v67, v138, v142
	v_cvt_pk_bf16_f32 v69, v148, v151
	v_mfma_f32_32x32x16_bf16 v[50:65], v[70:73], v[102:105], v[50:65]
	ds_read_b128 v[70:73], v90 offset:2560
	ds_read_b128 v[78:81], v90 offset:4608
	ds_read_b128 v[82:85], v90 offset:6656
	ds_read_b128 v[86:89], v90 offset:8704
	ds_read_b128 v[90:93], v90 offset:10752
	s_waitcnt lgkmcnt(4)
	v_mfma_f32_32x32x16_bf16 v[34:49], v[70:73], v[114:117], v[34:49]
	v_cvt_pk_bf16_f32 v70, v137, v139
	v_cvt_pk_bf16_f32 v71, v140, v144
	v_cvt_pk_bf16_f32 v72, v145, v149
	v_cvt_pk_bf16_f32 v73, v150, v152
	s_waitcnt lgkmcnt(3)
	v_mfma_f32_32x32x16_bf16 v[34:49], v[78:81], v[110:113], v[34:49]
	v_cvt_pk_bf16_f32 v78, v153, v154
	v_cvt_pk_bf16_f32 v79, v155, v156
	v_cvt_pk_bf16_f32 v80, v157, v158
	v_cvt_pk_bf16_f32 v81, v159, v160
	v_mfma_f32_32x32x16_bf16 v[50:65], v[74:77], v[98:101], v[50:65]
	v_add_f32_e32 v74, v143, v161
	v_add_f32_e32 v74, v147, v74
	v_add_f32_e32 v74, v148, v74
	v_add_f32_e32 v74, v151, v74
	v_add_f32_e32 v74, v137, v74
	v_add_f32_e32 v74, v139, v74
	v_add_f32_e32 v74, v140, v74
	s_waitcnt lgkmcnt(2)
	v_mfma_f32_32x32x16_bf16 v[34:49], v[82:85], v[106:109], v[34:49]
	v_add_f32_e32 v66, v144, v74
	v_add_f32_e32 v66, v145, v66
	v_add_f32_e32 v66, v149, v66
	v_add_f32_e32 v66, v150, v66
	v_add_f32_e32 v66, v152, v66
	v_add_f32_e32 v66, v94, v66
	v_add_f32_e32 v66, v95, v66
	s_waitcnt lgkmcnt(1)
	v_mfma_f32_32x32x16_bf16 v[34:49], v[86:89], v[102:105], v[34:49]
	v_add_f32_e32 v66, v96, v66
	v_add_f32_e32 v66, v97, v66
	v_add_f32_e32 v66, v130, v66
	v_add_f32_e32 v66, v131, v66
	v_add_f32_e32 v66, v134, v66
	v_add_f32_e32 v66, v135, v66
	v_add_f32_e32 v66, v153, v66
	s_waitcnt lgkmcnt(0)
	v_mfma_f32_32x32x16_bf16 v[34:49], v[90:93], v[98:101], v[34:49]
	v_add_f32_e32 v66, v154, v66
	v_add_f32_e32 v66, v155, v66
	v_add_f32_e32 v66, v156, v66
	v_add_f32_e32 v66, v157, v66
	v_add_f32_e32 v66, v158, v66
	v_add_f32_e32 v110, v159, v66
	v_cvt_pk_bf16_f32 v66, v141, v146
	v_cvt_pk_bf16_f32 v74, v94, v95
	v_cvt_pk_bf16_f32 v75, v96, v97
	v_cvt_pk_bf16_f32 v76, v130, v131
	v_cvt_pk_bf16_f32 v77, v134, v135
	v_add_u32_e32 v90, s53, v133
	ds_read_b64_tr_b16 v[82:83], v90 offset:12288
	ds_read_b64_tr_b16 v[84:85], v90 offset:12800
	ds_read_b64_tr_b16 v[86:87], v90 offset:16384
	s_waitcnt lgkmcnt(1)
	v_mfma_f32_32x32x16_bf16 v[18:33], v[82:85], v[66:69], v[18:33]
	ds_read_b64_tr_b16 v[88:89], v90 offset:16896
	ds_read_b64_tr_b16 v[82:83], v90 offset:13312
	s_waitcnt lgkmcnt(1)
	v_mfma_f32_32x32x16_bf16 v[2:17], v[86:89], v[66:69], v[2:17]
	ds_read_b64_tr_b16 v[84:85], v90 offset:13824
	ds_read_b64_tr_b16 v[66:67], v90 offset:17408
	s_waitcnt lgkmcnt(1)
	v_mfma_f32_32x32x16_bf16 v[18:33], v[82:85], v[70:73], v[18:33]
	ds_read_b64_tr_b16 v[68:69], v90 offset:17920
	ds_read_b64_tr_b16 v[82:83], v90 offset:14336
	s_waitcnt lgkmcnt(1)
	v_mfma_f32_32x32x16_bf16 v[2:17], v[66:69], v[70:73], v[2:17]
	ds_read_b64_tr_b16 v[84:85], v90 offset:14848
	ds_read_b64_tr_b16 v[66:67], v90 offset:15360
	ds_read_b64_tr_b16 v[68:69], v90 offset:15872
	ds_read_b64_tr_b16 v[70:71], v90 offset:18432
	ds_read_b64_tr_b16 v[72:73], v90 offset:18944
	ds_read_b64_tr_b16 v[86:87], v90 offset:19456
	ds_read_b64_tr_b16 v[88:89], v90 offset:19968
	s_waitcnt lgkmcnt(6)
	v_mfma_f32_32x32x16_bf16 v[18:33], v[82:85], v[74:77], v[18:33]
	v_max_f32_e32 v82, v35, v35
	v_max_f32_e32 v83, v51, v51
	v_max_f32_e32 v82, v83, v82
	v_max3_f32 v83, v50, v34, v52
	v_max3_f32 v82, v82, v53, v37
	v_max3_f32 v83, v83, v36, v54
	v_max3_f32 v82, v82, v55, v39
	s_waitcnt lgkmcnt(2)
	v_mfma_f32_32x32x16_bf16 v[2:17], v[70:73], v[74:77], v[2:17]
	v_max3_f32 v70, v83, v38, v56
	v_max3_f32 v71, v82, v57, v41
	v_max3_f32 v70, v70, v40, v58
	v_max3_f32 v71, v71, v59, v43
	v_max3_f32 v70, v70, v42, v60
	v_max3_f32 v71, v71, v61, v45
	v_max3_f32 v70, v70, v44, v62
	v_mfma_f32_32x32x16_bf16 v[18:33], v[66:69], v[78:81], v[18:33]
	v_max3_f32 v66, v71, v63, v47
	v_max3_f32 v67, v70, v46, v64
	v_max3_f32 v66, v66, v65, v49
	v_add_f32_e32 v68, v160, v110
	v_max3_f32 v66, v67, v48, v66
	v_add_f32_e32 v68, v136, v68
	v_cmp_lt_f32_e32 vcc, s33, v66
	s_waitcnt lgkmcnt(0)
	v_mfma_f32_32x32x16_bf16 v[2:17], v[86:89], v[78:81], v[2:17]
	s_cbranch_vccz .LBB0_436
	v_mov_b32_e32 v67, v66
	s_nop 1
	v_permlane32_swap_b32 v66, v67
	s_nop 1
	s_nop 0
	v_max3_f32 v66, v66, v67, 0
	v_exp_f32_e64 v70, -v66
	v_pk_add_f32 v[50:51], v[50:51], v[66:67] op_sel_hi:[1,0] neg_lo:[0,1] neg_hi:[0,1]
	v_pk_add_f32 v[52:53], v[52:53], v[66:67] op_sel_hi:[1,0] neg_lo:[0,1] neg_hi:[0,1]
	v_pk_add_f32 v[54:55], v[54:55], v[66:67] op_sel_hi:[1,0] neg_lo:[0,1] neg_hi:[0,1]
	v_pk_add_f32 v[56:57], v[56:57], v[66:67] op_sel_hi:[1,0] neg_lo:[0,1] neg_hi:[0,1]
	v_pk_add_f32 v[58:59], v[58:59], v[66:67] op_sel_hi:[1,0] neg_lo:[0,1] neg_hi:[0,1]
	v_pk_add_f32 v[60:61], v[60:61], v[66:67] op_sel_hi:[1,0] neg_lo:[0,1] neg_hi:[0,1]
	v_pk_add_f32 v[62:63], v[62:63], v[66:67] op_sel_hi:[1,0] neg_lo:[0,1] neg_hi:[0,1]
	v_pk_add_f32 v[64:65], v[64:65], v[66:67] op_sel_hi:[1,0] neg_lo:[0,1] neg_hi:[0,1]
	v_sub_f32_e32 v49, v49, v66
	v_sub_f32_e32 v48, v48, v66
	v_sub_f32_e32 v47, v47, v66
	v_sub_f32_e32 v46, v46, v66
	v_sub_f32_e32 v45, v45, v66
	v_sub_f32_e32 v44, v44, v66
	v_sub_f32_e32 v43, v43, v66
	v_sub_f32_e32 v42, v42, v66
	v_sub_f32_e32 v41, v41, v66
	v_sub_f32_e32 v40, v40, v66
	v_sub_f32_e32 v39, v39, v66
	v_sub_f32_e32 v38, v38, v66
	v_sub_f32_e32 v37, v37, v66
	v_sub_f32_e32 v36, v36, v66
	v_sub_f32_e32 v35, v35, v66
	v_sub_f32_e32 v34, v34, v66
	v_pk_mul_f32 v[32:33], v[32:33], v[70:71] op_sel_hi:[1,0]
	v_pk_mul_f32 v[30:31], v[30:31], v[70:71] op_sel_hi:[1,0]
	v_pk_mul_f32 v[28:29], v[28:29], v[70:71] op_sel_hi:[1,0]
	v_pk_mul_f32 v[26:27], v[26:27], v[70:71] op_sel_hi:[1,0]
	v_pk_mul_f32 v[24:25], v[24:25], v[70:71] op_sel_hi:[1,0]
	v_pk_mul_f32 v[22:23], v[22:23], v[70:71] op_sel_hi:[1,0]
	v_pk_mul_f32 v[20:21], v[20:21], v[70:71] op_sel_hi:[1,0]
	v_pk_mul_f32 v[18:19], v[18:19], v[70:71] op_sel_hi:[1,0]
	v_pk_mul_f32 v[16:17], v[16:17], v[70:71] op_sel_hi:[1,0]
	v_pk_mul_f32 v[14:15], v[14:15], v[70:71] op_sel_hi:[1,0]
	v_pk_mul_f32 v[12:13], v[12:13], v[70:71] op_sel_hi:[1,0]
	v_pk_mul_f32 v[10:11], v[10:11], v[70:71] op_sel_hi:[1,0]
	v_pk_mul_f32 v[8:9], v[8:9], v[70:71] op_sel_hi:[1,0]
	v_pk_mul_f32 v[6:7], v[6:7], v[70:71] op_sel_hi:[1,0]
	v_pk_mul_f32 v[4:5], v[4:5], v[70:71] op_sel_hi:[1,0]
	v_pk_mul_f32 v[2:3], v[2:3], v[70:71] op_sel_hi:[1,0]
	v_mul_f32_e32 v68, v68, v70
